# v27 + nt hint on once-read loads in phase 3c (y, r/k/v/g records) and phase 6 (p, x)
# speedup vs baseline: 1.0271x; 1.0109x over previous
; __device__ __forceinline__ void phase3c(const Params& p) {
;     ...
;     for (int it = blockIdx.x; it < 32 * 64; it += gridDim.x) {
;         const int bh = it >> 6, c4 = it & 63, b = bh >> 3, h = bh & 7;
;         const int c = h * 64 + sub * 4;
;         const f32x4 gain = *(const f32x4*)(p.in[14] + c), bias = *(const f32x4*)(p.in[15] + c), rk = *(const f32x4*)(p.in[13] + c);
;         u32x2 yb2[U]; f32x4 y[U]; h16x4 r4[U], k4[U], v4[U]; u32x2 g2[U];
; #pragma unroll
;         for (int u = 0; u < U; ++u) {
;             const int t = NMETA + (c4 * U + u) * 32 + (tid >> 4);
;             const size_t base = ((size_t)bh * TP + t) * 64 + sub * 4;
;             const size_t rec = ((size_t)bh * TP + t) * 448, pbase = rec + (sub & 3) * 16 + (sub >> 2) * 4;
;             yb2[u] = *(const u32x2*)(Y + base);
;             r4[u] = *(const h16x4*)(SI + SI_R * 64 + pbase); k4[u] = *(const h16x4*)(SI + SI_K * 64 + pbase); v4[u] = *(const h16x4*)(SI + SI_V * 64 + rec + sub * 4);
;             g2[u] = *(const u32x2*)((const bf16_t*)SI + 6 * 64 + pbase);
;         }
.LBB0_953:
	s_and_b32 s4, s25, 0x1c0
	s_and_b32 s1, s20, 0x1f80
	s_ashr_i32 s0, s25, 6
	s_and_b32 s5, s17, 0xffffe000
	s_waitcnt vmcnt(0)
	v_or_b32_e32 v27, s4, v9
	v_or_b32_e32 v10, s1, v34
	v_or_b32_e32 v0, s5, v169
	v_lshlrev_b32_e32 v28, 2, v27
	v_mad_i64_i32 v[24:25], s[4:5], s0, v35, v[10:11]
	v_mov_b32_e32 v19, v11
	v_mov_b32_e32 v21, v11
	v_add_u32_e32 v18, 32, v10
	v_add_u32_e32 v20, 64, v10
	v_or_b32_e32 v26, s1, v0
	global_load_dwordx4 v[0:3], v28, s[84:85]
	global_load_dwordx4 v[4:7], v28, s[86:87]
	global_load_dwordx4 v[36:39], v28, s[82:83]
	v_mad_u64_u32 v[28:29], s[4:5], v24, s22, 0
	v_lshlrev_b64 v[30:31], 7, v[24:25]
	v_add_u32_e32 v10, 0x60, v10
	v_mad_i64_i32 v[32:33], s[4:5], s0, v35, v[18:19]
	v_mad_i64_i32 v[20:21], s[4:5], s0, v35, v[20:21]
	v_or_b32_e32 v42, 64, v26
	v_mov_b32_e32 v18, v29
	v_lshl_add_u64 v[30:31], v[12:13], 0, v[30:31]
	v_mad_i64_i32 v[40:41], s[0:1], s0, v35, v[10:11]
	v_lshlrev_b32_e32 v10, 1, v27
	v_add_u32_e32 v44, 0x60, v26
	v_mad_u64_u32 v[52:53], s[0:1], v20, s22, 0
	v_ashrrev_i32_e32 v43, 31, v42
	v_mad_u64_u32 v[24:25], s[0:1], v25, s22, v[18:19]
	global_load_dwordx2 v[30:31], v[30:31], off nt
	v_or_b32_e32 v46, v28, v8
	v_lshlrev_b64 v[54:55], 7, v[20:21]
	v_mad_u64_u32 v[56:57], s[0:1], v40, s22, 0
	v_lshl_add_u64 v[60:61], s[44:45], 0, v[10:11]
	v_ashrrev_i32_e32 v45, 31, v44
	v_mov_b32_e32 v20, v53
	v_lshlrev_b64 v[42:43], 10, v[42:43]
	v_mov_b32_e32 v47, v24
	v_mad_u64_u32 v[48:49], s[0:1], v32, s22, 0
	v_lshlrev_b64 v[50:51], 7, v[32:33]
	v_mov_b32_e32 v62, v57
	v_lshlrev_b64 v[44:45], 10, v[44:45]
	v_mad_u64_u32 v[68:69], s[0:1], v21, s22, v[20:21]
	v_lshl_add_u64 v[20:21], v[60:61], 0, v[42:43]
	v_lshlrev_b64 v[42:43], 1, v[46:47]
	v_mov_b32_e32 v10, v49
	v_lshl_add_u64 v[50:51], v[12:13], 0, v[50:51]
	v_mov_b32_e32 v29, v24
	v_mad_u64_u32 v[62:63], s[0:1], v41, s22, v[62:63]
	v_lshl_add_u64 v[24:25], v[60:61], 0, v[44:45]
	v_lshl_add_u64 v[44:45], s[8:9], 0, v[42:43]
	v_lshl_add_u64 v[46:47], s[10:11], 0, v[42:43]
	v_lshl_add_u64 v[42:43], s[14:15], 0, v[42:43]
	v_ashrrev_i32_e32 v27, 31, v26
	v_mad_u64_u32 v[66:67], s[0:1], v33, s22, v[10:11]
	v_lshl_add_u64 v[28:29], v[28:29], 1, v[14:15]
	v_mov_b32_e32 v57, v62
	v_mov_b32_e32 v65, v62
	global_load_dwordx2 v[44:45], v[44:45], off nt
	s_nop 0
	global_load_dwordx2 v[46:47], v[46:47], off nt
	s_nop 0
	global_load_dwordx2 v[42:43], v[42:43], off nt
	s_nop 0
	global_load_dwordx2 v[62:63], v[28:29], off nt
	s_nop 0
	global_load_dwordx2 v[50:51], v[50:51], off nt
	v_lshlrev_b64 v[58:59], 7, v[40:41]
	v_lshlrev_b64 v[26:27], 10, v[26:27]
	v_or_b32_e32 v32, v48, v8
	v_or_b32_e32 v40, v52, v8
	v_or_b32_e32 v64, v56, v8
	v_mov_b32_e32 v33, v66
	v_mov_b32_e32 v41, v68
	v_lshl_add_u64 v[18:19], v[60:61], 0, v[26:27]
	v_mov_b32_e32 v49, v66
	v_mov_b32_e32 v53, v68
	v_lshlrev_b64 v[32:33], 1, v[32:33]
	v_lshlrev_b64 v[40:41], 1, v[40:41]
	v_lshlrev_b64 v[60:61], 1, v[64:65]
	v_lshl_add_u64 v[54:55], v[12:13], 0, v[54:55]
	v_lshl_add_u64 v[58:59], v[12:13], 0, v[58:59]
	v_lshl_add_u64 v[48:49], v[48:49], 1, v[14:15]
	v_lshl_add_u64 v[52:53], v[52:53], 1, v[14:15]
	v_lshl_add_u64 v[56:57], v[56:57], 1, v[14:15]
	v_lshl_add_u64 v[28:29], s[8:9], 0, v[32:33]
	v_lshl_add_u64 v[64:65], s[10:11], 0, v[32:33]
	v_lshl_add_u64 v[66:67], s[8:9], 0, v[40:41]
	v_lshl_add_u64 v[68:69], s[10:11], 0, v[40:41]
	v_lshl_add_u64 v[40:41], s[14:15], 0, v[40:41]
	v_lshl_add_u64 v[70:71], s[8:9], 0, v[60:61]
	v_lshl_add_u64 v[72:73], s[10:11], 0, v[60:61]
	v_lshl_add_u64 v[60:61], s[14:15], 0, v[60:61]
	global_load_dwordx2 v[48:49], v[48:49], off nt
	v_lshl_add_u64 v[32:33], s[14:15], 0, v[32:33]
	global_load_dwordx2 v[74:75], v[28:29], off nt
	s_nop 0
	global_load_dwordx2 v[64:65], v[64:65], off nt
	s_nop 0
	global_load_dwordx2 v[76:77], v[32:33], off nt
	s_nop 0
	global_load_dwordx2 v[54:55], v[54:55], off nt
	s_nop 0
	global_load_dwordx2 v[66:67], v[66:67], off nt
	s_nop 0
	global_load_dwordx2 v[68:69], v[68:69], off nt
	s_nop 0
	global_load_dwordx2 v[40:41], v[40:41], off nt
	s_nop 0
	global_load_dwordx2 v[52:53], v[52:53], off nt
	s_nop 0
	global_load_dwordx2 v[58:59], v[58:59], off nt
	s_nop 0
	global_load_dwordx2 v[70:71], v[70:71], off nt
	s_nop 0
	global_load_dwordx2 v[72:73], v[72:73], off nt
	s_nop 0
	global_load_dwordx2 v[60:61], v[60:61], off nt
	s_nop 0
	global_load_dwordx2 v[56:57], v[56:57], off nt
	s_add_i32 s17, s17, s19
	v_add_co_u32_e32 v26, vcc, s24, v18
	v_mov_b64_e32 v[22:23], s[18:19]
	s_nop 0
	v_addc_co_u32_e32 v27, vcc, 0, v19, vcc
	s_add_i32 s25, s25, s92
	s_add_i32 s20, s20, s21
	s_cmpk_lt_i32 s25, 0x800
	s_waitcnt vmcnt(19)
	v_lshlrev_b32_e32 v33, 16, v31
	v_lshlrev_b32_e32 v32, 16, v30
	v_and_b32_e32 v79, 0xffff0000, v31
	v_and_b32_e32 v78, 0xffff0000, v30
	v_pk_add_f32 v[28:29], v[32:33], v[78:79]
	s_waitcnt vmcnt(18)
	v_cvt_f32_f16_e32 v80, v44
	v_add_f32_e32 v10, v28, v29
	v_cvt_f32_f16_sdwa v81, v44 dst_sel:DWORD dst_unused:UNUSED_PAD src0_sel:WORD_1
	s_waitcnt vmcnt(17)
	v_cvt_f32_f16_e32 v82, v46
	v_add_f32_dpp v10, v10, v10 quad_perm:[1,0,3,2] row_mask:0xf bank_mask:0xf bound_ctrl:1
	v_cvt_f32_f16_sdwa v83, v46 dst_sel:DWORD dst_unused:UNUSED_PAD src0_sel:WORD_1
	s_waitcnt vmcnt(16)
	v_lshlrev_b32_e32 v28, 16, v42
	v_add_f32_dpp v10, v10, v10 quad_perm:[2,3,0,1] row_mask:0xf bank_mask:0xf bound_ctrl:1
	v_and_b32_e32 v29, 0xffff0000, v42
	s_waitcnt vmcnt(15)
	v_cvt_f32_f16_e32 v84, v62
	v_cvt_f32_f16_sdwa v85, v62 dst_sel:DWORD dst_unused:UNUSED_PAD src0_sel:WORD_1
	v_lshlrev_b32_e32 v30, 16, v43
	v_and_b32_e32 v31, 0xffff0000, v43
	v_cvt_f32_f16_e32 v42, v63
	v_cvt_f32_f16_sdwa v43, v63 dst_sel:DWORD dst_unused:UNUSED_PAD src0_sel:WORD_1
	s_waitcnt vmcnt(14)
; __device__ __forceinline__ void phase3c(const Params& p) {
;     ...
;         for (int u = 0; u < U; ++u) {
;             const int t = NMETA + (c4 * U + u) * 32 + (tid >> 4);
;             y[u][0] = __uint_as_float(yb2[u].x << 16); y[u][1] = __uint_as_float(yb2[u].x & 0xffff0000u); y[u][2] = __uint_as_float(yb2[u].y << 16); y[u][3] = __uint_as_float(yb2[u].y & 0xffff0000u);
;             const float mean = reduce16((y[u][0] + y[u][1]) + (y[u][2] + y[u][3])) * (1.0f / 64.0f);
;             const f32x4 dy = y[u] - mean;
;             const float var = reduce16((dy[0] * dy[0] + dy[1] * dy[1]) + (dy[2] * dy[2] + dy[3] * dy[3])) * (1.0f / 64.0f);
;             const float rs = rsqrtf(var + GN_EPS);
;             float bs = 0.f;
; #pragma unroll
;             for (int j = 0; j < 4; ++j) bs += (float)r4[u][j] * (float)k4[u][j] * rk[j];
;             bs = reduce16(bs);
;             const float gg[4] = {__uint_as_float(g2[u].x << 16), __uint_as_float(g2[u].x & 0xffff0000u), __uint_as_float(g2[u].y << 16), __uint_as_float(g2[u].y & 0xffff0000u)};
	v_lshlrev_b32_e32 v63, 16, v51
	v_lshlrev_b32_e32 v62, 16, v50
	v_and_b32_e32 v51, 0xffff0000, v51
	v_and_b32_e32 v50, 0xffff0000, v50
	v_cvt_f32_f16_e32 v44, v45
	v_cvt_f32_f16_sdwa v45, v45 dst_sel:DWORD dst_unused:UNUSED_PAD src0_sel:WORD_1
	v_cvt_f32_f16_e32 v46, v47
	v_cvt_f32_f16_sdwa v47, v47 dst_sel:DWORD dst_unused:UNUSED_PAD src0_sel:WORD_1
	v_add_f32_dpp v10, v10, v10 row_half_mirror row_mask:0xf bank_mask:0xf bound_ctrl:1
	v_pk_add_f32 v[88:89], v[62:63], v[50:51]
	s_waitcnt vmcnt(12)
	v_cvt_f32_f16_e32 v90, v74
	v_cvt_f32_f16_sdwa v91, v74 dst_sel:DWORD dst_unused:UNUSED_PAD src0_sel:WORD_1
	s_waitcnt vmcnt(11)
	v_cvt_f32_f16_e32 v92, v64
	v_cvt_f32_f16_sdwa v93, v64 dst_sel:DWORD dst_unused:UNUSED_PAD src0_sel:WORD_1
	v_cvt_f32_f16_e32 v74, v75
	v_cvt_f32_f16_sdwa v75, v75 dst_sel:DWORD dst_unused:UNUSED_PAD src0_sel:WORD_1
	v_cvt_f32_f16_e32 v64, v65
	v_cvt_f32_f16_sdwa v65, v65 dst_sel:DWORD dst_unused:UNUSED_PAD src0_sel:WORD_1
	s_waitcnt vmcnt(9)
	v_lshlrev_b32_e32 v97, 16, v55
	v_lshlrev_b32_e32 v96, 16, v54
	v_and_b32_e32 v55, 0xffff0000, v55
	v_and_b32_e32 v54, 0xffff0000, v54
	s_waitcnt vmcnt(8)
	v_cvt_f32_f16_e32 v98, v66
	v_cvt_f32_f16_sdwa v99, v66 dst_sel:DWORD dst_unused:UNUSED_PAD src0_sel:WORD_1
	s_waitcnt vmcnt(7)
	v_cvt_f32_f16_e32 v100, v68
	v_cvt_f32_f16_sdwa v101, v68 dst_sel:DWORD dst_unused:UNUSED_PAD src0_sel:WORD_1
	s_waitcnt vmcnt(4)
	v_lshlrev_b32_e32 v107, 16, v59
	v_lshlrev_b32_e32 v106, 16, v58
	v_and_b32_e32 v59, 0xffff0000, v59
	v_and_b32_e32 v58, 0xffff0000, v58
	v_cvt_f32_f16_e32 v66, v67
	v_cvt_f32_f16_sdwa v67, v67 dst_sel:DWORD dst_unused:UNUSED_PAD src0_sel:WORD_1
	v_cvt_f32_f16_e32 v68, v69
	v_cvt_f32_f16_sdwa v69, v69 dst_sel:DWORD dst_unused:UNUSED_PAD src0_sel:WORD_1
	s_waitcnt vmcnt(3)
	v_cvt_f32_f16_e32 v108, v70
	v_cvt_f32_f16_sdwa v109, v70 dst_sel:DWORD dst_unused:UNUSED_PAD src0_sel:WORD_1
	s_waitcnt vmcnt(2)
	v_cvt_f32_f16_e32 v110, v72
	v_cvt_f32_f16_sdwa v111, v72 dst_sel:DWORD dst_unused:UNUSED_PAD src0_sel:WORD_1
	v_cvt_f32_f16_e32 v70, v71
	v_cvt_f32_f16_sdwa v71, v71 dst_sel:DWORD dst_unused:UNUSED_PAD src0_sel:WORD_1
	v_cvt_f32_f16_e32 v72, v73
	v_cvt_f32_f16_sdwa v73, v73 dst_sel:DWORD dst_unused:UNUSED_PAD src0_sel:WORD_1
	v_add_f32_dpp v10, v10, v10 row_mirror row_mask:0xf bank_mask:0xf bound_ctrl:1
	v_add_f32_e32 v118, v88, v89
	v_pk_add_f32 v[88:89], v[96:97], v[54:55]
	v_pk_add_f32 v[116:117], v[106:107], v[58:59]
	v_fmac_f32_e32 v78, 0xbc800000, v10
	v_fmac_f32_e32 v32, 0xbc800000, v10
	v_fmac_f32_e32 v79, 0xbc800000, v10
	v_fmac_f32_e32 v33, 0xbc800000, v10
	v_add_f32_dpp v10, v118, v118 quad_perm:[1,0,3,2] row_mask:0xf bank_mask:0xf bound_ctrl:1
	v_add_f32_e32 v118, v88, v89
	v_add_f32_e32 v116, v116, v117
	v_mov_b32_e32 v88, v33
	v_mov_b32_e32 v89, v79
	v_mov_b32_e32 v33, v78
	v_pk_mul_f32 v[78:79], v[80:81], v[82:83]
	v_add_f32_dpp v10, v10, v10 quad_perm:[2,3,0,1] row_mask:0xf bank_mask:0xf bound_ctrl:1
	v_add_f32_dpp v117, v118, v118 quad_perm:[1,0,3,2] row_mask:0xf bank_mask:0xf bound_ctrl:1
	v_add_f32_dpp v116, v116, v116 quad_perm:[1,0,3,2] row_mask:0xf bank_mask:0xf bound_ctrl:1
	v_pk_mul_f32 v[44:45], v[44:45], v[46:47]
	v_pk_mul_f32 v[46:47], v[88:89], v[88:89]
	v_pk_mul_f32 v[80:81], v[32:33], v[32:33]
	v_pk_mul_f32 v[78:79], v[36:37], v[78:79]
	v_add_f32_dpp v10, v10, v10 row_half_mirror row_mask:0xf bank_mask:0xf bound_ctrl:1
	v_pk_mul_f32 v[82:83], v[90:91], v[92:93]
	v_pk_mul_f32 v[64:65], v[74:75], v[64:65]
	v_add_f32_dpp v90, v117, v117 quad_perm:[2,3,0,1] row_mask:0xf bank_mask:0xf bound_ctrl:1
	v_pk_mul_f32 v[74:75], v[98:99], v[100:101]
	v_add_f32_dpp v91, v116, v116 quad_perm:[2,3,0,1] row_mask:0xf bank_mask:0xf bound_ctrl:1
	v_pk_mul_f32 v[66:67], v[66:67], v[68:69]
	v_pk_mul_f32 v[68:69], v[108:109], v[110:111]
	v_pk_mul_f32 v[70:71], v[70:71], v[72:73]
	v_pk_mov_b32 v[72:73], v[80:81], v[46:47] op_sel:[1,0]
	v_mov_b32_e32 v81, v47
	v_add_f32_e32 v78, 0, v78
	v_add_f32_dpp v10, v10, v10 row_mirror row_mask:0xf bank_mask:0xf bound_ctrl:1
	v_pk_mul_f32 v[46:47], v[36:37], v[82:83]
	v_add_f32_dpp v82, v90, v90 row_half_mirror row_mask:0xf bank_mask:0xf bound_ctrl:1
	v_pk_mul_f32 v[74:75], v[36:37], v[74:75]
	v_add_f32_dpp v83, v91, v91 row_half_mirror row_mask:0xf bank_mask:0xf bound_ctrl:1
	v_pk_mul_f32 v[44:45], v[38:39], v[44:45]
	v_pk_mul_f32 v[64:65], v[38:39], v[64:65]
	v_pk_mul_f32 v[66:67], v[38:39], v[66:67]
	v_pk_mul_f32 v[36:37], v[36:37], v[68:69]
	v_pk_mul_f32 v[38:39], v[38:39], v[70:71]
	v_pk_add_f32 v[68:69], v[72:73], v[80:81]
	v_add_f32_e32 v70, v79, v78
	v_fmac_f32_e32 v50, 0xbc800000, v10
	v_fmac_f32_e32 v62, 0xbc800000, v10
	v_fmac_f32_e32 v51, 0xbc800000, v10
	v_fmac_f32_e32 v63, 0xbc800000, v10
	v_add_f32_e32 v10, 0, v46
	v_add_f32_dpp v46, v82, v82 row_mirror row_mask:0xf bank_mask:0xf bound_ctrl:1
	v_add_f32_e32 v72, 0, v74
	v_add_f32_dpp v73, v83, v83 row_mirror row_mask:0xf bank_mask:0xf bound_ctrl:1
	v_add_f32_e32 v36, 0, v36
	v_add_f32_e32 v44, v44, v70
	v_mov_b32_e32 v70, v63
	v_mov_b32_e32 v71, v51
	v_mov_b32_e32 v63, v50
	v_add_f32_e32 v10, v47, v10
	v_fmac_f32_e32 v54, 0xbc800000, v46
	v_fmac_f32_e32 v55, 0xbc800000, v46
	v_fmac_f32_e32 v97, 0xbc800000, v46
	v_add_f32_e32 v50, v75, v72
	v_fmac_f32_e32 v58, 0xbc800000, v73
	v_fmac_f32_e32 v59, 0xbc800000, v73
	v_fmac_f32_e32 v107, 0xbc800000, v73
	v_mov_b32_e32 v51, v68
	v_fmac_f32_e32 v96, 0xbc800000, v46
	v_fmac_f32_e32 v106, 0xbc800000, v73
	v_add_f32_e32 v68, v37, v36
	v_add_f32_e32 v72, v45, v44
	v_pk_mul_f32 v[36:37], v[70:71], v[70:71]
	v_pk_mul_f32 v[44:45], v[62:63], v[62:63]
	v_add_f32_e32 v10, v64, v10
	v_mov_b32_e32 v46, v97
	v_mov_b32_e32 v47, v55
; __device__ __forceinline__ void phase3c(const Params& p) {
;     ...
;             const float mean = reduce16((y[u][0] + y[u][1]) + (y[u][2] + y[u][3])) * (1.0f / 64.0f);
;             const f32x4 dy = y[u] - mean;
;             const float var = reduce16((dy[0] * dy[0] + dy[1] * dy[1]) + (dy[2] * dy[2] + dy[3] * dy[3])) * (1.0f / 64.0f);
;             const float rs = rsqrtf(var + GN_EPS);
;             float bs = 0.f;
; #pragma unroll
;             for (int j = 0; j < 4; ++j) bs += (float)r4[u][j] * (float)k4[u][j] * rk[j];
;             bs = reduce16(bs);
	v_mov_b32_e32 v97, v54
	v_add_f32_e32 v50, v66, v50
	v_mov_b32_e32 v54, v107
	v_mov_b32_e32 v55, v59
	v_mov_b32_e32 v107, v58
	v_add_f32_e32 v38, v38, v68
	v_add_f32_dpp v68, v72, v72 quad_perm:[1,0,3,2] row_mask:0xf bank_mask:0xf bound_ctrl:1
	v_pk_mov_b32 v[58:59], v[44:45], v[36:37] op_sel:[1,0]
	v_mov_b32_e32 v45, v37
	v_add_f32_e32 v10, v65, v10
	v_pk_mul_f32 v[36:37], v[46:47], v[46:47]
	v_pk_mul_f32 v[64:65], v[96:97], v[96:97]
	v_add_f32_e32 v50, v67, v50
	v_pk_mul_f32 v[66:67], v[54:55], v[54:55]
	v_pk_mul_f32 v[72:73], v[106:107], v[106:107]
	v_add_f32_e32 v74, v39, v38
	v_add_f32_dpp v68, v68, v68 quad_perm:[2,3,0,1] row_mask:0xf bank_mask:0xf bound_ctrl:1
	v_pk_add_f32 v[38:39], v[58:59], v[44:45]
	v_pk_mov_b32 v[44:45], v[64:65], v[36:37] op_sel:[1,0]
	v_mov_b32_e32 v65, v37
	v_pk_mov_b32 v[36:37], v[72:73], v[66:67] op_sel:[1,0]
	v_mov_b32_e32 v73, v67
	v_add_f32_dpp v58, v50, v50 quad_perm:[1,0,3,2] row_mask:0xf bank_mask:0xf bound_ctrl:1
	v_add_f32_dpp v66, v68, v68 row_half_mirror row_mask:0xf bank_mask:0xf bound_ctrl:1
	v_mov_b32_e32 v50, v38
	v_mov_b32_e32 v68, v39
	v_pk_add_f32 v[38:39], v[44:45], v[64:65]
	v_pk_add_f32 v[36:37], v[36:37], v[72:73]
	v_pk_add_f32 v[44:45], v[50:51], v[68:69]
	v_mov_b32_e32 v50, v36
	v_mov_b32_e32 v51, v38
	v_mov_b32_e32 v38, v37
	v_add_f32_dpp v10, v10, v10 quad_perm:[1,0,3,2] row_mask:0xf bank_mask:0xf bound_ctrl:1
	v_mov_b32_dpp v37, v45 quad_perm:[1,0,3,2] row_mask:0xf bank_mask:0xf bound_ctrl:1
	v_mov_b32_dpp v36, v44 quad_perm:[1,0,3,2] row_mask:0xf bank_mask:0xf bound_ctrl:1
	v_pk_add_f32 v[38:39], v[50:51], v[38:39]
	v_add_f32_dpp v67, v10, v10 quad_perm:[2,3,0,1] row_mask:0xf bank_mask:0xf bound_ctrl:1
	v_pk_add_f32 v[36:37], v[44:45], v[36:37]
	v_mov_b32_dpp v45, v39 quad_perm:[1,0,3,2] row_mask:0xf bank_mask:0xf bound_ctrl:1
	v_mov_b32_dpp v44, v38 quad_perm:[1,0,3,2] row_mask:0xf bank_mask:0xf bound_ctrl:1
	v_add_f32_dpp v10, v66, v66 row_mirror row_mask:0xf bank_mask:0xf bound_ctrl:1
	v_add_f32_dpp v64, v67, v67 row_half_mirror row_mask:0xf bank_mask:0xf bound_ctrl:1
	v_mov_b32_dpp v67, v37 quad_perm:[2,3,0,1] row_mask:0xf bank_mask:0xf bound_ctrl:1
	v_mov_b32_dpp v66, v36 quad_perm:[2,3,0,1] row_mask:0xf bank_mask:0xf bound_ctrl:1
	v_pk_add_f32 v[38:39], v[38:39], v[44:45]
	v_pk_add_f32 v[36:37], v[36:37], v[66:67]
	v_add_f32_dpp v59, v74, v74 quad_perm:[1,0,3,2] row_mask:0xf bank_mask:0xf bound_ctrl:1
	v_mov_b32_dpp v45, v39 quad_perm:[2,3,0,1] row_mask:0xf bank_mask:0xf bound_ctrl:1
	v_mov_b32_dpp v44, v38 quad_perm:[2,3,0,1] row_mask:0xf bank_mask:0xf bound_ctrl:1
	v_mov_b32_dpp v67, v37 row_half_mirror row_mask:0xf bank_mask:0xf bound_ctrl:1
	v_mov_b32_dpp v66, v36 row_half_mirror row_mask:0xf bank_mask:0xf bound_ctrl:1
	v_pk_add_f32 v[38:39], v[38:39], v[44:45]
	v_pk_add_f32 v[36:37], v[36:37], v[66:67]
	v_cvt_f32_f16_e32 v86, v48
	v_mov_b32_dpp v45, v39 row_half_mirror row_mask:0xf bank_mask:0xf bound_ctrl:1
	v_mov_b32_dpp v44, v38 row_half_mirror row_mask:0xf bank_mask:0xf bound_ctrl:1
	v_mov_b32_dpp v67, v37 row_mirror row_mask:0xf bank_mask:0xf bound_ctrl:1
	v_mov_b32_dpp v66, v36 row_mirror row_mask:0xf bank_mask:0xf bound_ctrl:1
	v_pk_add_f32 v[38:39], v[38:39], v[44:45]
	v_pk_add_f32 v[36:37], v[36:37], v[66:67]
	v_cvt_f32_f16_sdwa v87, v48 dst_sel:DWORD dst_unused:UNUSED_PAD src0_sel:WORD_1
	v_mov_b32_dpp v45, v39 row_mirror row_mask:0xf bank_mask:0xf bound_ctrl:1
	v_mov_b32_dpp v44, v38 row_mirror row_mask:0xf bank_mask:0xf bound_ctrl:1
	v_pk_fma_f32 v[36:37], v[36:37], s[16:17], v[16:17] op_sel_hi:[1,0,0]
	v_pk_add_f32 v[38:39], v[38:39], v[44:45]
	v_mul_f32_e32 v44, 0x4b800000, v37
	v_mul_f32_e32 v45, 0x4b800000, v36
	v_cmp_gt_f32_e32 vcc, s23, v36
	v_pk_fma_f32 v[22:23], v[38:39], s[16:17], v[22:23] op_sel_hi:[1,0,0]
	v_cmp_gt_f32_e64 s[0:1], s23, v37
	v_cndmask_b32_e32 v36, v36, v45, vcc
	v_mul_f32_e32 v38, 0x4b800000, v23
	v_cndmask_b32_e64 v37, v37, v44, s[0:1]
	v_cmp_gt_f32_e64 s[6:7], s23, v23
	v_mul_f32_e32 v39, 0x4b800000, v22
	v_cmp_gt_f32_e64 s[4:5], s23, v22
	v_rsq_f32_e32 v37, v37
	v_rsq_f32_e32 v36, v36
	v_cndmask_b32_e64 v23, v23, v38, s[6:7]
	v_cndmask_b32_e64 v22, v22, v39, s[4:5]
	v_rsq_f32_e32 v44, v23
	v_rsq_f32_e32 v45, v22
	v_cvt_f32_f16_e32 v48, v49
	v_cvt_f32_f16_sdwa v49, v49 dst_sel:DWORD dst_unused:UNUSED_PAD src0_sel:WORD_1
	v_add_f32_dpp v59, v59, v59 quad_perm:[2,3,0,1] row_mask:0xf bank_mask:0xf bound_ctrl:1
	v_mul_f32_e32 v22, 0x45800000, v37
	v_mul_f32_e32 v23, 0x45800000, v36
	v_cvt_f32_f16_e32 v104, v52
	v_cvt_f32_f16_sdwa v105, v52 dst_sel:DWORD dst_unused:UNUSED_PAD src0_sel:WORD_1
	v_cvt_f32_f16_e32 v52, v53
	v_cvt_f32_f16_sdwa v53, v53 dst_sel:DWORD dst_unused:UNUSED_PAD src0_sel:WORD_1
	v_add_f32_dpp v59, v59, v59 row_half_mirror row_mask:0xf bank_mask:0xf bound_ctrl:1
	v_cndmask_b32_e64 v22, v37, v22, s[0:1]
	v_cndmask_b32_e32 v36, v36, v23, vcc
	v_mul_f32_e32 v51, 0x45800000, v44
	s_waitcnt vmcnt(0)
; __device__ __forceinline__ unsigned pk_bf16(float lo, float hi) { const f32x2 v = {lo, hi}; return __builtin_bit_cast(unsigned, __builtin_convertvector(v, b16x2)); }
; __device__ __forceinline__ void phase3c(const Params& p) {
;     ...
;             const float rs = rsqrtf(var + GN_EPS);
;             float bs = 0.f;
; #pragma unroll
;             for (int j = 0; j < 4; ++j) bs += (float)r4[u][j] * (float)k4[u][j] * rk[j];
;             bs = reduce16(bs);
;             const float gg[4] = {__uint_as_float(g2[u].x << 16), __uint_as_float(g2[u].x & 0xffff0000u), __uint_as_float(g2[u].y << 16), __uint_as_float(g2[u].y & 0xffff0000u)};
;             float o[4];
; #pragma unroll
;             for (int j = 0; j < 4; ++j) o[j] = (dy[j] * rs * gain[j] + bias[j] + bs * (float)v4[u][j]) * gg[j];
;             u32x2 w; w.x = pk_bf16(o[0], o[1]); w.y = pk_bf16(o[2], o[3]);
;             *(u32x2*)(orw + (size_t)(b * SEQ + t - NMETA) * 512 + c) = w;
	v_cvt_f32_f16_e32 v114, v56
	v_cvt_f32_f16_sdwa v115, v56 dst_sel:DWORD dst_unused:UNUSED_PAD src0_sel:WORD_1
	v_cvt_f32_f16_e32 v56, v57
	v_cvt_f32_f16_sdwa v57, v57 dst_sel:DWORD dst_unused:UNUSED_PAD src0_sel:WORD_1
	v_add_f32_dpp v58, v58, v58 quad_perm:[2,3,0,1] row_mask:0xf bank_mask:0xf bound_ctrl:1
	v_add_f32_dpp v50, v59, v59 row_mirror row_mask:0xf bank_mask:0xf bound_ctrl:1
	v_mul_f32_e32 v59, 0x45800000, v45
	v_pk_mul_f32 v[32:33], v[32:33], v[22:23] op_sel_hi:[1,0]
	v_pk_mul_f32 v[22:23], v[88:89], v[22:23] op_sel_hi:[1,0]
	v_pk_mul_f32 v[38:39], v[62:63], v[36:37] op_sel_hi:[1,0]
	v_pk_mul_f32 v[36:37], v[70:71], v[36:37] op_sel_hi:[1,0]
	v_cndmask_b32_e64 v44, v44, v51, s[6:7]
	v_add_f32_dpp v65, v58, v58 row_half_mirror row_mask:0xf bank_mask:0xf bound_ctrl:1
	v_add_f32_dpp v58, v64, v64 row_mirror row_mask:0xf bank_mask:0xf bound_ctrl:1
	v_cndmask_b32_e64 v62, v45, v59, s[4:5]
	v_pk_fma_f32 v[32:33], v[0:1], v[32:33], v[4:5]
	v_pk_fma_f32 v[22:23], v[2:3], v[22:23], v[6:7]
	v_pk_fma_f32 v[38:39], v[0:1], v[38:39], v[4:5]
	v_pk_fma_f32 v[36:37], v[2:3], v[36:37], v[6:7]
	v_pk_mul_f32 v[66:67], v[96:97], v[44:45] op_sel_hi:[1,0]
	v_pk_mul_f32 v[44:45], v[46:47], v[44:45] op_sel_hi:[1,0]
	v_lshlrev_b32_e32 v94, 16, v76
	v_and_b32_e32 v95, 0xffff0000, v76
	v_lshlrev_b32_e32 v76, 16, v77
	v_and_b32_e32 v77, 0xffff0000, v77
	v_add_f32_dpp v64, v65, v65 row_mirror row_mask:0xf bank_mask:0xf bound_ctrl:1
	v_pk_mul_f32 v[46:47], v[106:107], v[62:63] op_sel_hi:[1,0]
	v_pk_mul_f32 v[54:55], v[54:55], v[62:63] op_sel_hi:[1,0]
	v_pk_fma_f32 v[32:33], v[10:11], v[84:85], v[32:33] op_sel_hi:[0,1,1]
	v_pk_fma_f32 v[22:23], v[10:11], v[42:43], v[22:23] op_sel_hi:[0,1,1]
	v_pk_fma_f32 v[38:39], v[58:59], v[86:87], v[38:39] op_sel_hi:[0,1,1]
	v_pk_fma_f32 v[36:37], v[58:59], v[48:49], v[36:37] op_sel_hi:[0,1,1]
	v_pk_fma_f32 v[42:43], v[0:1], v[66:67], v[4:5]
	v_pk_fma_f32 v[44:45], v[2:3], v[44:45], v[6:7]
	v_lshlrev_b32_e32 v102, 16, v40
	v_and_b32_e32 v103, 0xffff0000, v40
	v_lshlrev_b32_e32 v40, 16, v41
	v_and_b32_e32 v41, 0xffff0000, v41
	v_pk_fma_f32 v[0:1], v[0:1], v[46:47], v[4:5]
	v_pk_fma_f32 v[2:3], v[2:3], v[54:55], v[6:7]
	v_pk_mul_f32 v[4:5], v[32:33], v[28:29]
	v_pk_mul_f32 v[6:7], v[22:23], v[30:31]
	v_pk_mul_f32 v[22:23], v[38:39], v[94:95]
	v_pk_mul_f32 v[28:29], v[36:37], v[76:77]
	v_pk_fma_f32 v[30:31], v[64:65], v[104:105], v[42:43] op_sel_hi:[0,1,1]
	v_pk_fma_f32 v[32:33], v[64:65], v[52:53], v[44:45] op_sel_hi:[0,1,1]
	v_lshlrev_b32_e32 v112, 16, v60
	v_and_b32_e32 v113, 0xffff0000, v60
	v_lshlrev_b32_e32 v60, 16, v61
	v_and_b32_e32 v61, 0xffff0000, v61
	v_pk_fma_f32 v[0:1], v[50:51], v[114:115], v[0:1] op_sel_hi:[0,1,1]
	v_pk_fma_f32 v[2:3], v[50:51], v[56:57], v[2:3] op_sel_hi:[0,1,1]
	v_cvt_pk_bf16_f32 v4, v4, v5
	v_cvt_pk_bf16_f32 v5, v6, v7
	v_cvt_pk_bf16_f32 v6, v22, v23
	v_cvt_pk_bf16_f32 v7, v28, v29
	v_pk_mul_f32 v[22:23], v[30:31], v[102:103]
	v_pk_mul_f32 v[28:29], v[32:33], v[40:41]
	v_pk_mul_f32 v[0:1], v[0:1], v[112:113]
	v_pk_mul_f32 v[2:3], v[2:3], v[60:61]
	global_store_dwordx2 v[18:19], v[4:5], off
	global_store_dwordx2 v[26:27], v[6:7], off
	v_cvt_pk_bf16_f32 v4, v22, v23
	v_cvt_pk_bf16_f32 v5, v28, v29
	v_cvt_pk_bf16_f32 v0, v0, v1
	v_cvt_pk_bf16_f32 v1, v2, v3
	global_store_dwordx2 v[20:21], v[4:5], off
	global_store_dwordx2 v[24:25], v[0:1], off
	s_cbranch_scc1 .LBB0_953

; __device__ __forceinline__ unsigned pk_bf16(float lo, float hi) { const f32x2 v = {lo, hi}; return __builtin_bit_cast(unsigned, __builtin_convertvector(v, b16x2)); }
;     __device__ __forceinline__ void row(int r, int col32, int fq, const f32x4& a00, const f32x4& a01, const f32x4& a10, const f32x4& a11) const { half(r, col32, fq, a00, a01); half(r, col32 + HALF, fq, a10, a11); }
;     __device__ __forceinline__ void row(int r, int col32, int fq, const f32x4& a00, const f32x4& a01, const f32x4& a10, const f32x4& a11) const { half(r, col32, fq, a00, a01); half(r, col32 + HALF, fq, a10, a11); }
; __device__ __forceinline__ void phase6(const Params& p) {
;     ...
;     for (int it = blockIdx.x; it < MS / 16; it += gridDim.x) {
;         const int row0 = it * 16 + (threadIdx.x >> 6) * 2;
;         f32x4 v[2][4], x[2][4];
; #pragma unroll
;         for (int r = 0; r < 2; ++r)
; #pragma unroll
;             for (int j = 0; j < 4; ++j) {
;                 { const u32x2 pb2 = *(const u32x2*)((const bf16_t*)(ws + O_P) + (size_t)(row0 + r) * D + 4 * lane + 256 * j);
;                   v[r][j] = (f32x4){__uint_as_float(pb2.x << 16), __uint_as_float(pb2.x & 0xffff0000u), __uint_as_float(pb2.y << 16), __uint_as_float(pb2.y & 0xffff0000u)}; }
;                 x[r][j] = *(const f32x4*)(p.in[0] + (size_t)(row0 + r) * D + 4 * lane + 256 * j);
;             }
; #pragma unroll
;         for (int r = 0; r < 2; ++r) {
;             const int row = row0 + r;
;             float ss = 0.f;
; #pragma unroll
;             for (int j = 0; j < 4; ++j) ss += (v[r][j][0] * v[r][j][0] + v[r][j][1] * v[r][j][1]) + (v[r][j][2] * v[r][j][2] + v[r][j][3] * v[r][j][3]);
;             const float rs = rsqrtf(wave_sum(ss) * (1.0f / D) + RMS_EPS);
;             float s2 = 0.f;
; #pragma unroll
;             for (int j = 0; j < 4; ++j) {
;                 v[r][j] = x[r][j] + v[r][j] * rs * g1[j];
;                 { u32x2 hb; hb.x = pk_bf16(v[r][j][0], v[r][j][1]); hb.y = pk_bf16(v[r][j][2], v[r][j][3]);
;                   *(u32x2*)((bf16_t*)(ws + O_H1B) + (size_t)row * D + 4 * lane + 256 * j) = hb;
;                   v[r][j] = (f32x4){__uint_as_float(hb.x << 16), __uint_as_float(hb.x & 0xffff0000u), __uint_as_float(hb.y << 16), __uint_as_float(hb.y & 0xffff0000u)}; }
;                 s2 += (v[r][j][0] * v[r][j][0] + v[r][j][1] * v[r][j][1]) + (v[r][j][2] * v[r][j][2] + v[r][j][3] * v[r][j][3]);
.LBB0_1184:
	v_ashrrev_i32_e32 v49, 31, v48
	v_lshlrev_b64 v[54:55], 11, v[48:49]
	v_lshl_add_u64 v[32:33], v[40:41], 0, v[54:55]
	global_load_dwordx2 v[34:35], v[32:33], off offset:1536 nt
	global_load_dwordx2 v[36:37], v[32:33], off nt
	global_load_dwordx2 v[38:39], v[32:33], off offset:512 nt
	global_load_dwordx2 v[56:57], v[32:33], off offset:1024 nt
	v_add_u32_e32 v32, 1, v48
	v_ashrrev_i32_e32 v33, 31, v32
	v_lshlrev_b64 v[52:53], 11, v[32:33]
	v_lshl_add_u64 v[58:59], v[40:41], 0, v[52:53]
	global_load_dwordx2 v[86:87], v[58:59], off offset:1536 nt
	v_lshlrev_b64 v[60:61], 12, v[48:49]
	v_lshl_add_u64 v[60:61], v[46:47], 0, v[60:61]
	global_load_dwordx4 v[62:65], v[60:61], off nt
	global_load_dwordx4 v[66:69], v[60:61], off offset:1024 nt
	global_load_dwordx4 v[70:73], v[60:61], off offset:2048 nt
	global_load_dwordx4 v[82:85], v[60:61], off offset:3072 nt
	global_load_dwordx2 v[106:107], v[58:59], off nt
	global_load_dwordx2 v[108:109], v[58:59], off offset:512 nt
	global_load_dwordx2 v[110:111], v[58:59], off offset:1024 nt
	v_lshlrev_b64 v[32:33], 12, v[32:33]
	s_add_i32 s7, s7, s92
	s_cmpk_lt_i32 s7, 0x800
	v_add_u32_e32 v48, s1, v48
	s_waitcnt vmcnt(11)
	v_lshlrev_b32_e32 v89, 16, v34
	s_waitcnt vmcnt(10)
	v_and_b32_e32 v95, 0xffff0000, v36
	v_and_b32_e32 v97, 0xffff0000, v37
	v_and_b32_e32 v91, 0xffff0000, v34
	v_lshlrev_b32_e32 v92, 16, v35
	v_and_b32_e32 v93, 0xffff0000, v35
	v_lshlrev_b32_e32 v94, 16, v36
	v_lshlrev_b32_e32 v96, 16, v37
	s_waitcnt vmcnt(9)
	v_lshlrev_b32_e32 v98, 16, v38
	v_and_b32_e32 v101, 0xffff0000, v39
	v_and_b32_e32 v100, 0xffff0000, v38
	v_mul_f32_e32 v34, v97, v97
	v_mul_f32_e32 v38, v95, v95
	v_mov_b32_e32 v35, v89
	v_lshlrev_b32_e32 v99, 16, v39
	s_waitcnt vmcnt(8)
	v_and_b32_e32 v103, 0xffff0000, v56
	v_and_b32_e32 v105, 0xffff0000, v57
	v_pk_mul_f32 v[36:37], v[100:101], v[100:101]
	v_pk_fma_f32 v[74:75], v[96:97], v[96:97], v[34:35] op_sel_hi:[1,1,0]
	v_pk_fma_f32 v[38:39], v[94:95], v[94:95], v[38:39] op_sel_hi:[1,1,0]
	v_lshlrev_b32_e32 v102, 16, v56
	v_lshlrev_b32_e32 v104, 16, v57
	v_mul_f32_e32 v56, v103, v103
	v_mul_f32_e32 v60, v105, v105
	v_pk_fma_f32 v[36:37], v[98:99], v[98:99], v[36:37]
	v_mov_b32_e32 v88, v38
	v_mov_b32_e32 v34, v74
	v_mul_f32_e32 v49, v91, v91
	v_mul_f32_e32 v81, v92, v92
	v_mul_f32_e32 v90, v93, v93
	v_pk_fma_f32 v[56:57], v[102:103], v[102:103], v[56:57] op_sel_hi:[1,1,0]
	v_pk_fma_f32 v[60:61], v[104:105], v[104:105], v[60:61] op_sel_hi:[1,1,0]
	v_pk_add_f32 v[38:39], v[38:39], v[74:75]
	v_pk_add_f32 v[36:37], v[36:37], v[36:37] op_sel:[0,1] op_sel_hi:[1,0]
	v_pk_mul_f32 v[34:35], v[88:89], v[34:35]
	v_mov_b32_e32 v57, v81
	v_mov_b32_e32 v61, v90
	v_mov_b32_e32 v37, v49
	v_mov_b32_e32 v39, v35
	v_pk_add_f32 v[56:57], v[56:57], v[60:61]
	v_pk_add_f32 v[34:35], v[38:39], v[36:37]
	s_waitcnt vmcnt(7)
	v_lshlrev_b32_e32 v59, 16, v86
	v_pk_add_f32 v[34:35], v[34:35], v[56:57]
	v_and_b32_e32 v61, 0xffff0000, v86
	v_add_f32_e32 v34, v34, v35
	ds_bpermute_b32 v35, v51, v34
	v_and_b32_e32 v57, 0xffff0000, v87
	v_mov_b32_e32 v86, v98
	v_mov_b32_e32 v90, v89
	v_mov_b32_e32 v115, v59
	s_waitcnt lgkmcnt(0)
	v_add_f32_e32 v34, v34, v35
	ds_bpermute_b32 v35, v76, v34
	s_waitcnt vmcnt(0)
	v_and_b32_e32 v113, 0xffff0000, v110
	v_lshlrev_b32_e32 v112, 16, v110
	v_lshlrev_b32_e32 v110, 16, v111
	v_and_b32_e32 v111, 0xffff0000, v111
	s_waitcnt lgkmcnt(0)
	v_add_f32_e32 v34, v34, v35
	ds_bpermute_b32 v35, v77, v34
	v_mul_f32_e32 v81, v57, v57
	v_lshl_add_u64 v[74:75], v[46:47], 0, v[32:33]
	s_waitcnt lgkmcnt(0)
	v_add_f32_e32 v34, v34, v35
	ds_bpermute_b32 v35, v78, v34
	s_waitcnt lgkmcnt(0)
	v_add_f32_e32 v49, v34, v35
	ds_bpermute_b32 v56, v79, v49
	global_load_dwordx4 v[36:39], v[74:75], off nt
	global_load_dwordx4 v[32:35], v[74:75], off offset:1024 nt
	s_waitcnt lgkmcnt(0)
	v_add_f32_e32 v49, v49, v56
	ds_bpermute_b32 v58, v80, v49
	v_lshlrev_b32_e32 v56, 16, v87
	v_mov_b32_e32 v87, v100
	v_mov_b32_e32 v100, v99
	v_mul_f32_e32 v60, v56, v56
	s_waitcnt lgkmcnt(0)
	v_add_f32_e32 v49, v49, v58
	v_fmamk_f32 v49, v49, 0x3a800000, v50
	v_mul_f32_e32 v58, 0x4b800000, v49
	v_cmp_gt_f32_e32 vcc, s6, v49
	s_nop 1
	v_cndmask_b32_e32 v49, v49, v58, vcc
	v_rsq_f32_e32 v49, v49
	s_nop 0
	v_mul_f32_e32 v58, 0x45800000, v49
	v_cndmask_b32_e32 v58, v49, v58, vcc
	v_pk_mul_f32 v[88:89], v[58:59], v[94:95] op_sel_hi:[0,1]
	v_pk_mul_f32 v[94:95], v[58:59], v[96:97] op_sel_hi:[0,1]
	v_pk_mul_f32 v[86:87], v[58:59], v[86:87] op_sel_hi:[0,1]
	v_pk_mul_f32 v[96:97], v[58:59], v[100:101] op_sel_hi:[0,1]
	v_pk_mul_f32 v[90:91], v[58:59], v[90:91] op_sel_hi:[0,1]
	v_pk_mul_f32 v[92:93], v[58:59], v[92:93] op_sel_hi:[0,1]
	v_pk_fma_f32 v[64:65], v[2:3], v[94:95], v[64:65]
	v_pk_fma_f32 v[62:63], v[0:1], v[88:89], v[62:63]
	v_pk_fma_f32 v[68:69], v[6:7], v[96:97], v[68:69]
	v_pk_fma_f32 v[66:67], v[4:5], v[86:87], v[66:67]
	v_pk_mul_f32 v[98:99], v[58:59], v[102:103] op_sel_hi:[0,1]
	v_pk_mul_f32 v[100:101], v[58:59], v[104:105] op_sel_hi:[0,1]
	v_pk_fma_f32 v[84:85], v[14:15], v[92:93], v[84:85]
	v_pk_fma_f32 v[82:83], v[12:13], v[90:91], v[82:83]
	v_cvt_pk_bf16_f32 v90, v62, v63
	v_cvt_pk_bf16_f32 v91, v64, v65
	v_cvt_pk_bf16_f32 v92, v66, v67
	v_cvt_pk_bf16_f32 v93, v68, v69
	v_pk_fma_f32 v[72:73], v[10:11], v[100:101], v[72:73]
	v_pk_fma_f32 v[70:71], v[8:9], v[98:99], v[70:71]
	v_and_b32_e32 v99, 0xffff0000, v91
	v_and_b32_e32 v101, 0xffff0000, v90
	v_and_b32_e32 v63, 0xffff0000, v93
	v_and_b32_e32 v67, 0xffff0000, v92
	v_cvt_pk_bf16_f32 v94, v70, v71
	v_cvt_pk_bf16_f32 v96, v82, v83
	v_lshlrev_b32_e32 v98, 16, v91
	v_lshlrev_b32_e32 v100, 16, v90
	v_lshlrev_b32_e32 v62, 16, v93
	v_lshlrev_b32_e32 v66, 16, v92
; __device__ __forceinline__ unsigned pk_bf16(float lo, float hi) { const f32x2 v = {lo, hi}; return __builtin_bit_cast(unsigned, __builtin_convertvector(v, b16x2)); }
;     __device__ __forceinline__ void row(int r, int col32, int fq, const f32x4& a00, const f32x4& a01, const f32x4& a10, const f32x4& a11) const { half(r, col32, fq, a00, a01); half(r, col32 + HALF, fq, a10, a11); }
;     __device__ __forceinline__ void row(int r, int col32, int fq, const f32x4& a00, const f32x4& a01, const f32x4& a10, const f32x4& a11) const { half(r, col32, fq, a00, a01); half(r, col32 + HALF, fq, a10, a11); }
;     __device__ __forceinline__ void row(int r, int col32, int fq, const f32x4& a00, const f32x4& a01, const f32x4& a10, const f32x4& a11) const { half(r, col32, fq, a00, a01); half(r, col32 + HALF, fq, a10, a11); }
; __device__ __forceinline__ void phase6(const Params& p) {
;     ...
;         for (int r = 0; r < 2; ++r) {
;             const int row = row0 + r;
;             float ss = 0.f;
; #pragma unroll
;             for (int j = 0; j < 4; ++j) ss += (v[r][j][0] * v[r][j][0] + v[r][j][1] * v[r][j][1]) + (v[r][j][2] * v[r][j][2] + v[r][j][3] * v[r][j][3]);
;             const float rs = rsqrtf(wave_sum(ss) * (1.0f / D) + RMS_EPS);
;             float s2 = 0.f;
; #pragma unroll
;             for (int j = 0; j < 4; ++j) {
;                 v[r][j] = x[r][j] + v[r][j] * rs * g1[j];
;                 { u32x2 hb; hb.x = pk_bf16(v[r][j][0], v[r][j][1]); hb.y = pk_bf16(v[r][j][2], v[r][j][3]);
;                   *(u32x2*)((bf16_t*)(ws + O_H1B) + (size_t)row * D + 4 * lane + 256 * j) = hb;
;                   v[r][j] = (f32x4){__uint_as_float(hb.x << 16), __uint_as_float(hb.x & 0xffff0000u), __uint_as_float(hb.y << 16), __uint_as_float(hb.y & 0xffff0000u)}; }
;                 s2 += (v[r][j][0] * v[r][j][0] + v[r][j][1] * v[r][j][1]) + (v[r][j][2] * v[r][j][2] + v[r][j][3] * v[r][j][3]);
;             }
;             const float rs2 = rsqrtf(wave_sum(s2) * (1.0f / D) + RMS_EPS);
;             bf16_t* fr_ = (bf16_t*)(ws + O_F) + (size_t)row * D;
; #pragma unroll
;             for (int j = 0; j < 4; ++j) {
;                 u32x2 w; w.x = pk_bf16(v[r][j][0] * rs2 * g2[j][0], v[r][j][1] * rs2 * g2[j][1]); w.y = pk_bf16(v[r][j][2] * rs2 * g2[j][2], v[r][j][3] * rs2 * g2[j][3]);
;                 *(u32x2*)(fr_ + 4 * lane + 256 * j) = w;
	v_mov_b32_e32 v70, v101
	v_mov_b32_e32 v71, v99
	v_mov_b32_e32 v82, v67
	v_mov_b32_e32 v83, v63
	v_cvt_pk_bf16_f32 v95, v72, v73
	v_mov_b32_e32 v68, v100
	v_mov_b32_e32 v69, v98
	v_mov_b32_e32 v72, v66
	v_mov_b32_e32 v73, v62
	v_pk_mul_f32 v[70:71], v[70:71], v[70:71]
	v_pk_mul_f32 v[82:83], v[82:83], v[82:83]
	v_lshlrev_b32_e32 v64, 16, v95
	v_pk_fma_f32 v[68:69], v[68:69], v[68:69], v[70:71]
	v_pk_fma_f32 v[70:71], v[72:73], v[72:73], v[82:83]
	v_cvt_pk_bf16_f32 v97, v84, v85
	v_and_b32_e32 v65, 0xffff0000, v95
	v_mul_f32_e32 v58, v64, v64
	v_pk_add_f32 v[86:87], v[70:71], v[70:71] op_sel_hi:[0,1]
	v_lshlrev_b32_e32 v70, 16, v94
	v_pk_fma_f32 v[84:85], v[64:65], v[64:65], v[58:59] op_sel_hi:[1,1,0]
	v_pk_add_f32 v[82:83], v[68:69], v[68:69] op_sel_hi:[0,1]
	v_and_b32_e32 v71, 0xffff0000, v94
	v_mul_f32_e32 v58, v70, v70
	v_lshlrev_b32_e32 v68, 16, v97
	v_and_b32_e32 v69, 0xffff0000, v97
	v_lshlrev_b32_e32 v72, 16, v96
	v_and_b32_e32 v73, 0xffff0000, v96
	v_pk_fma_f32 v[88:89], v[70:71], v[70:71], v[58:59] op_sel_hi:[1,1,0]
	v_pk_mul_f32 v[102:103], v[68:69], v[68:69]
	v_pk_mul_f32 v[104:105], v[72:73], v[72:73]
	v_mov_b32_e32 v82, v102
	v_mov_b32_e32 v86, v103
	v_mov_b32_e32 v88, v104
	v_mov_b32_e32 v84, v105
	v_and_b32_e32 v105, 0xffff0000, v107
	v_pk_add_f32 v[82:83], v[82:83], v[86:87]
	v_pk_add_f32 v[84:85], v[88:89], v[84:85]
	v_and_b32_e32 v103, 0xffff0000, v106
	v_lshlrev_b32_e32 v104, 16, v107
	v_mul_f32_e32 v58, v105, v105
	v_pk_add_f32 v[82:83], v[84:85], v[82:83]
	v_lshlrev_b32_e32 v102, 16, v106
	v_pk_fma_f32 v[84:85], v[104:105], v[104:105], v[58:59] op_sel_hi:[1,1,0]
	v_lshlrev_b32_e32 v107, 16, v109
	v_lshlrev_b32_e32 v106, 16, v108
	v_and_b32_e32 v109, 0xffff0000, v109
	v_and_b32_e32 v108, 0xffff0000, v108
	v_mul_f32_e32 v58, v103, v103
	v_pk_mul_f32 v[86:87], v[108:109], v[108:109]
	v_pk_fma_f32 v[88:89], v[102:103], v[102:103], v[58:59] op_sel_hi:[1,1,0]
	v_pk_fma_f32 v[86:87], v[106:107], v[106:107], v[86:87]
	v_mov_b32_e32 v58, v88
	v_mov_b32_e32 v114, v84
	v_mul_f32_e32 v49, v61, v61
	v_pk_add_f32 v[84:85], v[88:89], v[84:85]
	v_pk_mul_f32 v[88:89], v[58:59], v[114:115]
	v_pk_add_f32 v[86:87], v[86:87], v[86:87] op_sel:[0,1] op_sel_hi:[1,0]
	v_mov_b32_e32 v85, v89
	v_mov_b32_e32 v87, v49
	v_mul_f32_e32 v58, v113, v113
	v_pk_add_f32 v[84:85], v[84:85], v[86:87]
	v_pk_fma_f32 v[86:87], v[112:113], v[112:113], v[58:59] op_sel_hi:[1,1,0]
	v_mul_f32_e32 v58, v111, v111
	v_pk_fma_f32 v[88:89], v[110:111], v[110:111], v[58:59] op_sel_hi:[1,1,0]
	v_mov_b32_e32 v87, v60
	v_mov_b32_e32 v89, v81
	v_pk_add_f32 v[86:87], v[86:87], v[88:89]
	s_nop 0
	v_pk_add_f32 v[84:85], v[84:85], v[86:87]
	v_mov_b32_e32 v87, v82
	v_mov_b32_e32 v86, v84
	v_mov_b32_e32 v82, v85
	v_pk_add_f32 v[86:87], v[86:87], v[82:83]
	ds_bpermute_b32 v89, v51, v87
	ds_bpermute_b32 v88, v51, v86
	global_load_dwordx4 v[82:85], v[74:75], off offset:2048 nt
	s_waitcnt lgkmcnt(0)
	v_pk_add_f32 v[114:115], v[86:87], v[88:89]
	global_load_dwordx4 v[86:89], v[74:75], off offset:3072 nt
	ds_bpermute_b32 v117, v76, v115
	ds_bpermute_b32 v116, v76, v114
	s_waitcnt lgkmcnt(0)
	v_pk_add_f32 v[74:75], v[114:115], v[116:117]
	ds_bpermute_b32 v115, v77, v75
	ds_bpermute_b32 v114, v77, v74
	v_lshl_add_u64 v[116:117], v[42:43], 0, v[54:55]
	global_store_dwordx2 v[116:117], v[90:91], off
	global_store_dwordx2 v[116:117], v[92:93], off offset:512
	v_lshl_add_u64 v[54:55], v[44:45], 0, v[54:55]
	global_store_dwordx2 v[116:117], v[94:95], off offset:1024
	global_store_dwordx2 v[116:117], v[96:97], off offset:1536
	s_waitcnt lgkmcnt(0)
	v_pk_add_f32 v[74:75], v[74:75], v[114:115]
	ds_bpermute_b32 v115, v78, v75
	ds_bpermute_b32 v114, v78, v74
	s_waitcnt lgkmcnt(0)
	v_pk_add_f32 v[74:75], v[74:75], v[114:115]
	ds_bpermute_b32 v115, v79, v75
	ds_bpermute_b32 v114, v79, v74
	s_waitcnt lgkmcnt(0)
	v_pk_add_f32 v[74:75], v[74:75], v[114:115]
	ds_bpermute_b32 v115, v80, v75
	ds_bpermute_b32 v114, v80, v74
	s_waitcnt lgkmcnt(0)
	v_pk_add_f32 v[74:75], v[74:75], v[114:115]
	s_nop 0
	v_pk_fma_f32 v[74:75], v[74:75], s[0:1], v[50:51] op_sel_hi:[1,0,0]
	s_nop 0
	v_mul_f32_e32 v49, 0x4b800000, v75
	v_cmp_gt_f32_e32 vcc, s6, v75
	s_nop 1
	v_cndmask_b32_e32 v49, v75, v49, vcc
	v_rsq_f32_e32 v49, v49
	s_nop 0
	v_mul_f32_e32 v58, 0x45800000, v49
	v_cndmask_b32_e32 v58, v49, v58, vcc
	v_mul_f32_e32 v49, 0x4b800000, v74
	v_cmp_gt_f32_e32 vcc, s6, v74
	v_pk_mul_f32 v[90:91], v[58:59], v[100:101] op_sel_hi:[0,1]
	v_pk_mul_f32 v[92:93], v[58:59], v[98:99] op_sel_hi:[0,1]
	v_cndmask_b32_e32 v49, v74, v49, vcc
	v_rsq_f32_e32 v49, v49
	v_pk_mul_f32 v[90:91], v[28:29], v[90:91]
	v_pk_mul_f32 v[74:75], v[30:31], v[92:93]
	v_cvt_pk_bf16_f32 v90, v90, v91
	v_mul_f32_e32 v60, 0x45800000, v49
	v_cvt_pk_bf16_f32 v91, v74, v75
	v_cndmask_b32_e32 v74, v49, v60, vcc
	global_store_dwordx2 v[54:55], v[90:91], off
	v_pk_mul_f32 v[90:91], v[74:75], v[102:103] op_sel_hi:[0,1]
	v_pk_mul_f32 v[92:93], v[74:75], v[104:105] op_sel_hi:[0,1]
	s_waitcnt vmcnt(8)
	v_pk_fma_f32 v[38:39], v[2:3], v[92:93], v[38:39]
	v_pk_fma_f32 v[36:37], v[0:1], v[90:91], v[36:37]
	v_mov_b32_e32 v60, v59
	v_cvt_pk_bf16_f32 v36, v36, v37
	v_cvt_pk_bf16_f32 v37, v38, v39
	v_mov_b32_e32 v38, v106
	v_mov_b32_e32 v39, v108
	v_mov_b32_e32 v108, v107
	v_pk_mul_f32 v[38:39], v[74:75], v[38:39] op_sel_hi:[0,1]
	v_pk_mul_f32 v[90:91], v[74:75], v[108:109] op_sel_hi:[0,1]
	s_waitcnt vmcnt(7)
	v_pk_fma_f32 v[34:35], v[6:7], v[90:91], v[34:35]
	v_pk_fma_f32 v[32:33], v[4:5], v[38:39], v[32:33]
	v_pk_mul_f32 v[38:39], v[74:75], v[110:111] op_sel_hi:[0,1]
	v_cvt_pk_bf16_f32 v32, v32, v33
	v_cvt_pk_bf16_f32 v33, v34, v35
	v_pk_mul_f32 v[34:35], v[74:75], v[112:113] op_sel_hi:[0,1]
	s_waitcnt vmcnt(6)
; __device__ __forceinline__ unsigned pk_bf16(float lo, float hi) { const f32x2 v = {lo, hi}; return __builtin_bit_cast(unsigned, __builtin_convertvector(v, b16x2)); }
;     __device__ __forceinline__ void row(int r, int col32, int fq, const f32x4& a00, const f32x4& a01, const f32x4& a10, const f32x4& a11) const { half(r, col32, fq, a00, a01); half(r, col32 + HALF, fq, a10, a11); }
;     __device__ __forceinline__ void row(int r, int col32, int fq, const f32x4& a00, const f32x4& a01, const f32x4& a10, const f32x4& a11) const { half(r, col32, fq, a00, a01); half(r, col32 + HALF, fq, a10, a11); }
;     __device__ __forceinline__ void row(int r, int col32, int fq, const f32x4& a00, const f32x4& a01, const f32x4& a10, const f32x4& a11) const { half(r, col32, fq, a00, a01); half(r, col32 + HALF, fq, a10, a11); }
; __device__ __forceinline__ void phase6(const Params& p) {
;     ...
;             float s2 = 0.f;
; #pragma unroll
;             for (int j = 0; j < 4; ++j) {
;                 v[r][j] = x[r][j] + v[r][j] * rs * g1[j];
;                 { u32x2 hb; hb.x = pk_bf16(v[r][j][0], v[r][j][1]); hb.y = pk_bf16(v[r][j][2], v[r][j][3]);
;                   *(u32x2*)((bf16_t*)(ws + O_H1B) + (size_t)row * D + 4 * lane + 256 * j) = hb;
;                   v[r][j] = (f32x4){__uint_as_float(hb.x << 16), __uint_as_float(hb.x & 0xffff0000u), __uint_as_float(hb.y << 16), __uint_as_float(hb.y & 0xffff0000u)}; }
;                 s2 += (v[r][j][0] * v[r][j][0] + v[r][j][1] * v[r][j][1]) + (v[r][j][2] * v[r][j][2] + v[r][j][3] * v[r][j][3]);
;             }
;             const float rs2 = rsqrtf(wave_sum(s2) * (1.0f / D) + RMS_EPS);
;             bf16_t* fr_ = (bf16_t*)(ws + O_F) + (size_t)row * D;
; #pragma unroll
;             for (int j = 0; j < 4; ++j) {
;                 u32x2 w; w.x = pk_bf16(v[r][j][0] * rs2 * g2[j][0], v[r][j][1] * rs2 * g2[j][1]); w.y = pk_bf16(v[r][j][2] * rs2 * g2[j][2], v[r][j][3] * rs2 * g2[j][3]);
;                 *(u32x2*)(fr_ + 4 * lane + 256 * j) = w;
	v_pk_fma_f32 v[38:39], v[10:11], v[38:39], v[84:85]
	v_pk_fma_f32 v[34:35], v[8:9], v[34:35], v[82:83]
	v_pk_mul_f32 v[56:57], v[74:75], v[56:57] op_sel_hi:[0,1]
	v_cvt_pk_bf16_f32 v34, v34, v35
	v_cvt_pk_bf16_f32 v35, v38, v39
	v_pk_mul_f32 v[38:39], v[74:75], v[60:61] op_sel_hi:[0,1]
	s_waitcnt vmcnt(5)
	v_pk_fma_f32 v[56:57], v[14:15], v[56:57], v[88:89]
	v_pk_fma_f32 v[38:39], v[12:13], v[38:39], v[86:87]
	v_and_b32_e32 v61, 0xffff0000, v36
	v_cvt_pk_bf16_f32 v38, v38, v39
	v_cvt_pk_bf16_f32 v39, v56, v57
	v_and_b32_e32 v57, 0xffff0000, v37
	v_lshlrev_b32_e32 v56, 16, v37
	v_lshlrev_b32_e32 v60, 16, v36
	v_mov_b32_e32 v82, v61
	v_mov_b32_e32 v83, v57
	v_mov_b32_e32 v74, v60
	v_mov_b32_e32 v75, v56
	v_pk_mul_f32 v[82:83], v[82:83], v[82:83]
	v_and_b32_e32 v85, 0xffff0000, v32
	v_pk_fma_f32 v[74:75], v[74:75], v[74:75], v[82:83]
	v_and_b32_e32 v83, 0xffff0000, v33
	v_lshlrev_b32_e32 v82, 16, v33
	v_lshlrev_b32_e32 v84, 16, v32
	v_mov_b32_e32 v88, v85
	v_mov_b32_e32 v89, v83
	v_mov_b32_e32 v86, v84
	v_mov_b32_e32 v87, v82
	v_pk_mul_f32 v[88:89], v[88:89], v[88:89]
	v_pk_add_f32 v[74:75], v[74:75], v[74:75] op_sel_hi:[0,1]
	v_pk_fma_f32 v[86:87], v[86:87], v[86:87], v[88:89]
	v_lshlrev_b32_e32 v88, 16, v35
	v_and_b32_e32 v89, 0xffff0000, v35
	v_mul_f32_e32 v74, v88, v88
	v_lshlrev_b32_e32 v92, 16, v34
	v_pk_fma_f32 v[90:91], v[88:89], v[88:89], v[74:75] op_sel_hi:[1,1,0]
	v_and_b32_e32 v93, 0xffff0000, v34
	v_mul_f32_e32 v74, v92, v92
	v_lshlrev_b32_e32 v96, 16, v39
	v_and_b32_e32 v97, 0xffff0000, v39
	v_lshlrev_b32_e32 v100, 16, v38
	v_and_b32_e32 v101, 0xffff0000, v38
	v_pk_add_f32 v[86:87], v[86:87], v[86:87] op_sel_hi:[0,1]
	v_pk_fma_f32 v[94:95], v[92:93], v[92:93], v[74:75] op_sel_hi:[1,1,0]
	v_pk_mul_f32 v[98:99], v[96:97], v[96:97]
	v_pk_mul_f32 v[102:103], v[100:101], v[100:101]
	v_mov_b32_e32 v74, v98
	v_mov_b32_e32 v86, v99
	v_mov_b32_e32 v94, v102
	v_mov_b32_e32 v90, v103
	v_pk_add_f32 v[74:75], v[74:75], v[86:87]
	v_pk_add_f32 v[86:87], v[94:95], v[90:91]
	s_nop 0
	v_pk_add_f32 v[74:75], v[86:87], v[74:75]
	s_nop 0
	v_add_f32_e32 v49, v74, v75
	ds_bpermute_b32 v59, v51, v49
	s_waitcnt lgkmcnt(0)
	v_add_f32_e32 v49, v49, v59
	v_pk_mul_f32 v[66:67], v[58:59], v[66:67] op_sel_hi:[0,1]
	v_pk_mul_f32 v[62:63], v[58:59], v[62:63] op_sel_hi:[0,1]
	ds_bpermute_b32 v59, v76, v49
	v_pk_mul_f32 v[66:67], v[24:25], v[66:67]
	v_pk_mul_f32 v[62:63], v[26:27], v[62:63]
	v_cvt_pk_bf16_f32 v66, v66, v67
	v_cvt_pk_bf16_f32 v67, v62, v63
	s_waitcnt lgkmcnt(0)
	v_add_f32_e32 v49, v49, v59
	v_pk_mul_f32 v[62:63], v[58:59], v[70:71] op_sel_hi:[0,1]
	ds_bpermute_b32 v59, v77, v49
	v_pk_mul_f32 v[62:63], v[20:21], v[62:63]
	global_store_dwordx2 v[54:55], v[66:67], off offset:512
	v_cvt_pk_bf16_f32 v62, v62, v63
	s_waitcnt lgkmcnt(0)
	v_add_f32_e32 v49, v49, v59
	v_pk_mul_f32 v[64:65], v[58:59], v[64:65] op_sel_hi:[0,1]
	ds_bpermute_b32 v59, v78, v49
	v_pk_mul_f32 v[64:65], v[22:23], v[64:65]
	s_waitcnt lgkmcnt(0)
	v_add_f32_e32 v49, v49, v59
	v_cvt_pk_bf16_f32 v63, v64, v65
	ds_bpermute_b32 v64, v79, v49
	global_store_dwordx2 v[54:55], v[62:63], off offset:1024
	v_pk_mul_f32 v[62:63], v[58:59], v[72:73] op_sel_hi:[0,1]
	v_pk_mul_f32 v[58:59], v[58:59], v[68:69] op_sel_hi:[0,1]
	v_pk_mul_f32 v[62:63], v[16:17], v[62:63]
	v_pk_mul_f32 v[58:59], v[18:19], v[58:59]
	s_waitcnt lgkmcnt(0)
	v_add_f32_e32 v49, v49, v64
	v_cvt_pk_bf16_f32 v62, v62, v63
	v_cvt_pk_bf16_f32 v63, v58, v59
	ds_bpermute_b32 v58, v80, v49
	global_store_dwordx2 v[54:55], v[62:63], off offset:1536
	v_lshl_add_u64 v[54:55], v[42:43], 0, v[52:53]
	global_store_dwordx2 v[54:55], v[36:37], off
	global_store_dwordx2 v[54:55], v[32:33], off offset:512
	global_store_dwordx2 v[54:55], v[34:35], off offset:1024
	global_store_dwordx2 v[54:55], v[38:39], off offset:1536
	s_waitcnt lgkmcnt(0)
	v_add_f32_e32 v32, v49, v58
	v_fmamk_f32 v32, v32, 0x3a800000, v50
	v_mul_f32_e32 v33, 0x4b800000, v32
	v_cmp_gt_f32_e32 vcc, s6, v32
	s_nop 1
	v_cndmask_b32_e32 v32, v32, v33, vcc
	v_rsq_f32_e32 v36, v32
	v_lshl_add_u64 v[32:33], v[44:45], 0, v[52:53]
	v_mul_f32_e32 v34, 0x45800000, v36
	v_cndmask_b32_e32 v34, v36, v34, vcc
	v_pk_mul_f32 v[36:37], v[34:35], v[60:61] op_sel_hi:[0,1]
	v_pk_mul_f32 v[38:39], v[34:35], v[56:57] op_sel_hi:[0,1]
	v_pk_mul_f32 v[36:37], v[28:29], v[36:37]
	v_pk_mul_f32 v[38:39], v[30:31], v[38:39]
	v_cvt_pk_bf16_f32 v36, v36, v37
	v_cvt_pk_bf16_f32 v37, v38, v39
	global_store_dwordx2 v[32:33], v[36:37], off
	v_pk_mul_f32 v[36:37], v[34:35], v[84:85] op_sel_hi:[0,1]
	v_pk_mul_f32 v[38:39], v[34:35], v[82:83] op_sel_hi:[0,1]
	v_pk_mul_f32 v[36:37], v[24:25], v[36:37]
	v_pk_mul_f32 v[38:39], v[26:27], v[38:39]
	v_cvt_pk_bf16_f32 v36, v36, v37
	v_cvt_pk_bf16_f32 v37, v38, v39
	global_store_dwordx2 v[32:33], v[36:37], off offset:512
	v_pk_mul_f32 v[36:37], v[34:35], v[92:93] op_sel_hi:[0,1]
	v_pk_mul_f32 v[38:39], v[34:35], v[88:89] op_sel_hi:[0,1]
	v_pk_mul_f32 v[36:37], v[20:21], v[36:37]
	v_pk_mul_f32 v[38:39], v[22:23], v[38:39]
	v_cvt_pk_bf16_f32 v36, v36, v37
	v_cvt_pk_bf16_f32 v37, v38, v39
	global_store_dwordx2 v[32:33], v[36:37], off offset:1024
	v_pk_mul_f32 v[36:37], v[34:35], v[100:101] op_sel_hi:[0,1]
	v_pk_mul_f32 v[34:35], v[34:35], v[96:97] op_sel_hi:[0,1]
	v_pk_mul_f32 v[36:37], v[16:17], v[36:37]
	v_pk_mul_f32 v[34:35], v[18:19], v[34:35]
	v_cvt_pk_bf16_f32 v36, v36, v37
	v_cvt_pk_bf16_f32 v37, v34, v35
	global_store_dwordx2 v[32:33], v[36:37], off offset:1536
	s_cbranch_scc1 .LBB0_1184
